# mixer A: interior key tiles skip the mask/clamp prelude (branch on the wave-uniform masked flag), 16 masked-only address ops moved behind the unmasked branch
# speedup vs baseline: 1.0082x; 1.0040x over previous
; template <bool MASKED>
; DI bool attnA_tile_math(const f32x16& Su, const LAS float* bt, int qpos, int kpos0, int kvalid, bool meta_tile, int h, int lane, float& m, float& l, float& corr, bf16x8 (&bfrag)[2]) {
;     ...
;         const int row = (r & 3) + 8 * (r >> 2) + 4 * h;
;         const int dist = qpos - (kpos0 + row);
;         if (MASKED) {
;             const bool vis = (row < kvalid) && (dist >= 0) && (meta_tile || dist < 128);
;             const int di = dist < 0 ? 0 : (dist > 128 ? 128 : dist);
;             const float v = Su[r] * (0.125f * 1.4426950408889634f) + bt[di];
;             sc[r] = vis ? v : -1e30f;
; DI void attnA_item(bf16_t* z, const float* sinks, int hp, int qs, LAS bf16_t* vs, const LAS float* btab, int lane) {
;     ...
;         const int kpos0 = t < 0 ? 0 : NMETA + 32 * t, kvalid = t < 0 ? NMETA : 32;
;         const bool lastt = metaq || t == thi;
;         const bool interior = !metaq && t >= 0 && t > qs - 4 && t < qs;
.LBB0_197:
	s_lshl_b32 s4, s31, 5
	s_or_b32 s6, s4, 16
	s_cmp_lt_i32 s31, 0
	s_cselect_b64 s[8:9], -1, 0
	s_and_b64 s[4:5], s[8:9], exec
	s_cselect_b32 s30, 16, 32
	s_cselect_b32 s42, 0, s6
	s_or_b32 s4, s31, s28
	s_cmp_lt_i32 s4, 0
	s_cselect_b64 s[4:5], -1, 0
	s_cmp_le_i32 s31, s86
	v_add_u32_e32 v211, s42, v125
	s_cselect_b64 s[6:7], -1, 0
	s_cmp_ge_i32 s31, s28
	v_sub_u32_e32 v186, v128, v211
	s_cselect_b64 s[10:11], -1, 0
	s_or_b64 s[4:5], s[6:7], s[4:5]
	v_cmp_gt_i32_e32 vcc, s30, v125
	v_cmp_lt_i32_e64 s[36:37], -1, v186
	v_add_u32_e32 v66, s42, v130
	s_or_b64 s[6:7], s[4:5], s[10:11]
	s_cbranch_scc0 .LfastA
	s_and_b64 s[4:5], vcc, s[36:37]
	v_cmp_gt_i32_e32 vcc, s15, v186
	v_sub_u32_e32 v66, v128, v66
	s_or_b64 s[10:11], s[8:9], vcc
	v_cmp_gt_i32_e32 vcc, s30, v130
	v_cmp_lt_i32_e64 s[38:39], -1, v66
	s_and_b64 s[36:37], s[4:5], s[10:11]
	s_and_b64 s[4:5], vcc, s[38:39]
	v_cmp_gt_i32_e32 vcc, s15, v66
	v_med3_i32 v173, v66, 0, v176
	v_add_u32_e32 v66, s42, v131
	v_sub_u32_e32 v66, v128, v66
	s_or_b64 s[10:11], s[8:9], vcc
	v_cmp_gt_i32_e32 vcc, s30, v131
	v_cmp_lt_i32_e64 s[40:41], -1, v66
	s_and_b64 s[38:39], s[4:5], s[10:11]
	s_and_b64 s[4:5], vcc, s[40:41]
	v_cmp_gt_i32_e32 vcc, s15, v66
	v_med3_i32 v182, v66, 0, v176
	v_add_u32_e32 v66, s42, v132
	v_sub_u32_e32 v66, v128, v66
	s_or_b64 s[10:11], s[8:9], vcc
	v_cmp_gt_i32_e32 vcc, s30, v132
	v_cmp_lt_i32_e64 s[42:43], -1, v66
	s_and_b64 s[40:41], s[4:5], s[10:11]
	s_and_b64 s[4:5], vcc, s[42:43]
	v_cmp_gt_i32_e32 vcc, s15, v66
	v_med3_i32 v183, v66, 0, v176
	v_sub_u32_e32 v66, v147, v211
	s_or_b64 s[10:11], s[8:9], vcc
	v_cmp_gt_i32_e32 vcc, s30, v133
	v_cmp_lt_i32_e64 s[42:43], -1, v66
	s_and_b64 s[44:45], s[4:5], s[10:11]
	s_and_b64 s[4:5], vcc, s[42:43]
	v_cmp_gt_i32_e32 vcc, s15, v66
	v_sub_u32_e32 v212, v148, v211
	s_or_b64 s[10:11], s[8:9], vcc
	v_cmp_gt_i32_e32 vcc, s30, v134
	v_cmp_lt_i32_e64 s[42:43], -1, v212
	s_and_b64 s[48:49], s[4:5], s[10:11]
	v_med3_i32 v184, v66, 0, v176
	s_and_b64 s[4:5], vcc, s[42:43]
	v_cmp_gt_i32_e32 vcc, s15, v212
	v_sub_u32_e32 v66, v149, v211
	s_or_b64 s[10:11], s[8:9], vcc
	v_cmp_gt_i32_e32 vcc, s30, v135
	v_cmp_lt_i32_e64 s[42:43], -1, v66
	s_and_b64 s[52:53], s[4:5], s[10:11]
	s_and_b64 s[4:5], vcc, s[42:43]
	v_cmp_gt_i32_e32 vcc, s15, v66
	v_sub_u32_e32 v213, v150, v211
	s_or_b64 s[10:11], s[8:9], vcc
	v_cmp_gt_i32_e32 vcc, s30, v136
	v_cmp_lt_i32_e64 s[42:43], -1, v213
	s_and_b64 s[56:57], s[4:5], s[10:11]
	v_med3_i32 v187, v66, 0, v176
	s_and_b64 s[4:5], vcc, s[42:43]
	v_cmp_gt_i32_e32 vcc, s15, v213
	v_sub_u32_e32 v66, v151, v211
	s_or_b64 s[10:11], s[8:9], vcc
	v_cmp_gt_i32_e32 vcc, s30, v137
	v_cmp_lt_i32_e64 s[42:43], -1, v66
	s_and_b64 s[60:61], s[4:5], s[10:11]
	s_and_b64 s[4:5], vcc, s[42:43]
	v_cmp_gt_i32_e32 vcc, s15, v66
	v_sub_u32_e32 v214, v152, v211
	s_or_b64 s[10:11], s[8:9], vcc
	v_cmp_gt_i32_e32 vcc, s30, v138
	v_cmp_lt_i32_e64 s[46:47], -1, v214
	s_and_b64 s[42:43], s[4:5], s[10:11]
	v_med3_i32 v189, v66, 0, v176
	s_and_b64 s[4:5], vcc, s[46:47]
	v_cmp_gt_i32_e32 vcc, s15, v214
	v_sub_u32_e32 v66, v153, v211
	s_or_b64 s[10:11], s[8:9], vcc
	v_cmp_gt_i32_e32 vcc, s30, v139
	v_cmp_lt_i32_e64 s[50:51], -1, v66
	s_and_b64 s[46:47], s[4:5], s[10:11]
	s_and_b64 s[4:5], vcc, s[50:51]
	v_cmp_gt_i32_e32 vcc, s15, v66
	v_sub_u32_e32 v210, v158, v211
	s_or_b64 s[10:11], s[8:9], vcc
	v_cmp_gt_i32_e32 vcc, s30, v140
	v_cmp_lt_i32_e64 s[54:55], -1, v210
	s_and_b64 s[50:51], s[4:5], s[10:11]
	v_med3_i32 v191, v66, 0, v176
	s_and_b64 s[4:5], vcc, s[54:55]
	v_cmp_gt_i32_e32 vcc, s15, v210
	v_sub_u32_e32 v66, v159, v211
	s_or_b64 s[10:11], s[8:9], vcc
	v_cmp_gt_i32_e32 vcc, s30, v141
	v_cmp_lt_i32_e64 s[58:59], -1, v66
	s_and_b64 s[54:55], s[4:5], s[10:11]
	s_and_b64 s[4:5], vcc, s[58:59]
	v_cmp_gt_i32_e32 vcc, s15, v66
	v_sub_u32_e32 v209, v160, v211
	s_or_b64 s[10:11], s[8:9], vcc
	v_cmp_gt_i32_e32 vcc, s30, v142
	v_cmp_lt_i32_e64 s[62:63], -1, v209
	s_and_b64 s[58:59], s[4:5], s[10:11]
	v_med3_i32 v205, v66, 0, v176
	s_and_b64 s[4:5], vcc, s[62:63]
	v_cmp_gt_i32_e32 vcc, s15, v209
	v_sub_u32_e32 v66, v161, v211
	s_or_b64 s[10:11], s[8:9], vcc
	v_cmp_gt_i32_e32 vcc, s30, v143
	v_cmp_lt_i32_e64 s[64:65], -1, v66
	s_and_b64 s[62:63], s[4:5], s[10:11]
	s_and_b64 s[4:5], vcc, s[64:65]
	v_cmp_gt_i32_e32 vcc, s15, v66
	v_med3_i32 v216, v66, 0, v176
	ds_read_b128 v[66:69], v129 offset:6144
	ds_read_b128 v[120:123], v129 offset:7168
	ds_read_b128 v[168:171], v129 offset:8192
	ds_read_b128 v[178:181], v129 offset:9216
	v_sub_u32_e32 v208, v162, v211
	s_or_b64 s[10:11], s[8:9], vcc
	v_cmp_gt_i32_e32 vcc, s30, v144
	v_cmp_lt_i32_e64 s[66:67], -1, v208
	s_and_b64 s[64:65], s[4:5], s[10:11]
	s_and_b64 s[4:5], vcc, s[66:67]
	v_cmp_gt_i32_e32 vcc, s15, v208
	s_waitcnt lgkmcnt(0)
	s_or_b64 s[10:11], s[8:9], vcc
	v_med3_i32 v0, v186, 0, v176
	v_med3_i32 v185, v212, 0, v176
	v_med3_i32 v188, v213, 0, v176
	v_med3_i32 v190, v214, 0, v176
	v_med3_i32 v192, v210, 0, v176
	s_and_b64 s[66:67], s[4:5], s[10:11]
	v_med3_i32 v215, v209, 0, v176
	v_med3_i32 v217, v208, 0, v176
; #define LAS __attribute__((address_space(3)))
; #define MFMA32(a, b, c) __builtin_amdgcn_mfma_f32_32x32x16_bf16((a), (b), (c), 0, 0, 0)
; template <bool MASKED>
; DI bool attnA_tile_math(const f32x16& Su, const LAS float* bt, int qpos, int kpos0, int kvalid, bool meta_tile, int h, int lane, float& m, float& l, float& corr, bf16x8 (&bfrag)[2]) {
;     float sc[16]; float tmax = -1e30f;
; #pragma unroll
;     for (int r = 0; r < 16; ++r) {
;         const int row = (r & 3) + 8 * (r >> 2) + 4 * h;
;         const int dist = qpos - (kpos0 + row);
;         if (MASKED) {
;             const bool vis = (row < kvalid) && (dist >= 0) && (meta_tile || dist < 128);
;             const int di = dist < 0 ? 0 : (dist > 128 ? 128 : dist);
;             const float v = Su[r] * (0.125f * 1.4426950408889634f) + bt[di];
;             sc[r] = vis ? v : -1e30f;
;         } else sc[r] = Su[r] * (0.125f * 1.4426950408889634f) + bt[dist];
;         tmax = fmaxf(tmax, sc[r]);
;     }
;     tmax = fmaxf(tmax, shflx(tmax, 32, lane));
;     const bool resc = __any(tmax > m + 16.0f);
;     float mnew = m; corr = 1.0f;
;     if (resc) { mnew = fmaxf(m, tmax); corr = __builtin_amdgcn_exp2f(m - mnew); }
;     float pr[16]; float psum = 0.f;
; #pragma unroll
;     for (int r = 0; r < 16; ++r) { pr[r] = __builtin_amdgcn_exp2f(sc[r] - mnew); psum += pr[r]; }
;     psum += shflx(psum, 32, lane);
; DI void attnA_item(bf16_t* z, const float* sinks, int hp, int qs, LAS bf16_t* vs, const LAS float* btab, int lane) {
;     ...
;             for (int s = 0; s < 4; ++s) qf[s] = qs_lds[64 * (4 * u + s)];
;             asm volatile("s_waitcnt lgkmcnt(0)" ::: "memory"); __builtin_amdgcn_sched_barrier(0);
;             __builtin_amdgcn_s_setprio(1);
; #pragma unroll
;             for (int s = 0; s < 4; ++s) Su = MFMA32(kf[s], qf[s], Su);
;             __builtin_amdgcn_s_setprio(0);
;             if (u == 1) {
; #pragma unroll
;                 for (int s = 0; s < 4; ++s) kf[s] = *(const bf16x8*)(kbase + ron + (((s >> 1) << 9) | ((s & 1) << 8)));
;             }
;             const LAS float* bt = btab + (2 * hp + u) * 129;
;             float corr; bool resc;
;             if (interior) resc = attnA_tile_math<false>(Su, bt, qpos, kpos0, kvalid, t < 0, h, lane, m[u], l[u], corr, bfrag[u]);
;             else resc = attnA_tile_math<true>(Su, bt, qpos, kpos0, kvalid, t < 0, h, lane, m[u], l[u], corr, bfrag[u]);
.LqkA:
	s_setprio 1
	s_waitcnt vmcnt(7) lgkmcnt(3)
	v_mfma_f32_32x32x16_bf16 v[66:81], v[94:97], v[66:69], 0
	s_waitcnt vmcnt(6) lgkmcnt(2)
	v_mfma_f32_32x32x16_bf16 v[66:81], v[90:93], v[120:123], v[66:81]
	s_waitcnt vmcnt(5) lgkmcnt(1)
	v_mfma_f32_32x32x16_bf16 v[66:81], v[86:89], v[168:171], v[66:81]
	s_waitcnt vmcnt(4) lgkmcnt(0)
	v_mfma_f32_32x32x16_bf16 v[66:81], v[82:85], v[178:181], v[66:81]
	s_setprio 0
	s_nop 10
	v_mul_f32_e32 v66, 0x3e38aa3b, v66
	s_mov_b64 s[10:11], -1
	s_and_b64 vcc, exec, s[6:7]
	v_add_f32_e32 v207, 0x41800000, v118
	v_max_f32_e32 v206, v118, v118
	s_cbranch_vccz .LBB0_199
	v_lshl_add_u32 v204, v0, 2, s87
	v_lshl_add_u32 v203, v173, 2, s87
	v_lshl_add_u32 v202, v182, 2, s87
	v_lshl_add_u32 v201, v183, 2, s87
	v_lshl_add_u32 v200, v184, 2, s87
	v_lshl_add_u32 v199, v185, 2, s87
	v_lshl_add_u32 v198, v187, 2, s87
	v_lshl_add_u32 v197, v188, 2, s87
	v_lshl_add_u32 v196, v189, 2, s87
	v_lshl_add_u32 v195, v190, 2, s87
	v_lshl_add_u32 v194, v191, 2, s87
	v_lshl_add_u32 v193, v192, 2, s87
	v_lshl_add_u32 v192, v205, 2, s87
	v_lshl_add_u32 v191, v215, 2, s87
	v_lshl_add_u32 v190, v216, 2, s87
	v_lshl_add_u32 v189, v217, 2, s87
	ds_read_b32 v0, v204
	ds_read_b32 v120, v203
	ds_read_b32 v121, v202
	ds_read_b32 v122, v201
	ds_read_b32 v123, v200
	ds_read_b32 v168, v199
	ds_read_b32 v169, v198
	ds_read_b32 v170, v197
	s_waitcnt lgkmcnt(7)
	v_add_f32_e32 v0, v66, v0
	s_waitcnt lgkmcnt(6)
	v_fmac_f32_e32 v120, 0x3e38aa3b, v67
	v_cndmask_b32_e64 v171, v177, v0, s[36:37]
	v_cndmask_b32_e64 v120, v177, v120, s[38:39]
	s_waitcnt lgkmcnt(5)
	v_fmac_f32_e32 v121, 0x3e38aa3b, v68
	s_waitcnt lgkmcnt(4)
	v_fmac_f32_e32 v122, 0x3e38aa3b, v69
	s_waitcnt lgkmcnt(3)
	v_fmac_f32_e32 v123, 0x3e38aa3b, v70
	s_waitcnt lgkmcnt(2)
	v_fmac_f32_e32 v168, 0x3e38aa3b, v71
	s_waitcnt lgkmcnt(1)
	v_fmac_f32_e32 v169, 0x3e38aa3b, v72
	s_waitcnt lgkmcnt(0)
	v_fmac_f32_e32 v170, 0x3e38aa3b, v73
	v_max3_f32 v0, v171, s18, v120
	v_cndmask_b32_e64 v173, v177, v121, s[40:41]
	v_cndmask_b32_e64 v122, v177, v122, s[44:45]
	v_cndmask_b32_e64 v178, v177, v123, s[48:49]
	v_cndmask_b32_e64 v179, v177, v168, s[52:53]
	v_cndmask_b32_e64 v180, v177, v169, s[56:57]
	v_cndmask_b32_e64 v181, v177, v170, s[60:61]
	ds_read_b32 v121, v196
	ds_read_b32 v123, v195
	ds_read_b32 v168, v194
	ds_read_b32 v169, v193
	ds_read_b32 v170, v192
	ds_read_b32 v182, v191
	ds_read_b32 v183, v190
	ds_read_b32 v184, v189
	v_max3_f32 v0, v0, v173, v122
	v_max3_f32 v0, v0, v178, v179
	s_waitcnt lgkmcnt(7)
	v_fmac_f32_e32 v121, 0x3e38aa3b, v74
	s_waitcnt lgkmcnt(6)
	v_fmac_f32_e32 v123, 0x3e38aa3b, v75
	v_max3_f32 v0, v0, v180, v181
	v_cndmask_b32_e64 v185, v177, v121, s[42:43]
	v_cndmask_b32_e64 v187, v177, v123, s[46:47]
	s_waitcnt lgkmcnt(5)
	v_fmac_f32_e32 v168, 0x3e38aa3b, v76
	s_waitcnt lgkmcnt(4)
	v_fmac_f32_e32 v169, 0x3e38aa3b, v77
	v_max3_f32 v0, v0, v185, v187
	v_cndmask_b32_e64 v188, v177, v168, s[50:51]
	v_cndmask_b32_e64 v205, v177, v169, s[54:55]
	s_waitcnt lgkmcnt(3)
	v_fmac_f32_e32 v170, 0x3e38aa3b, v78
	s_waitcnt lgkmcnt(2)
	v_fmac_f32_e32 v182, 0x3e38aa3b, v79
	v_max3_f32 v0, v0, v188, v205
	v_cndmask_b32_e64 v215, v177, v170, s[58:59]
	v_cndmask_b32_e64 v216, v177, v182, s[62:63]
	s_waitcnt lgkmcnt(1)
	v_fmac_f32_e32 v183, 0x3e38aa3b, v80
	s_waitcnt lgkmcnt(0)
	v_fmac_f32_e32 v184, 0x3e38aa3b, v81
	v_max3_f32 v0, v0, v215, v216
	v_cndmask_b32_e64 v217, v177, v183, s[64:65]
	v_cndmask_b32_e64 v218, v177, v184, s[66:67]
	v_max3_f32 v0, v0, v217, v218
	ds_bpermute_b32 v121, v145, v0
	s_mov_b64 s[10:11], 0
	s_waitcnt lgkmcnt(0)
	v_max_f32_e32 v121, v121, v121
	v_max_f32_e32 v0, v0, v121
	v_max_f32_e32 v121, v206, v0
	v_sub_f32_e32 v123, v118, v121
	v_exp_f32_e32 v123, v123
	v_cmp_gt_f32_e32 vcc, v0, v207
	s_cmp_lg_u64 vcc, 0
	s_cselect_b64 s[4:5], -1, 0
	v_cndmask_b32_e64 v121, v118, v121, s[4:5]
	v_cndmask_b32_e64 v0, 1.0, v123, s[4:5]
	v_sub_f32_e32 v123, v171, v121
	v_exp_f32_e32 v123, v123
	v_sub_f32_e32 v120, v120, v121
	v_exp_f32_e32 v168, v120
	v_sub_f32_e32 v120, v173, v121
	v_exp_f32_e32 v169, v120
	v_sub_f32_e32 v120, v122, v121
	v_exp_f32_e32 v122, v120
	v_add_f32_e32 v120, 0, v123
	v_add_f32_e32 v120, v168, v120
	v_add_f32_e32 v120, v169, v120
	v_add_f32_e32 v182, v122, v120
	v_sub_f32_e32 v120, v178, v121
	v_exp_f32_e32 v170, v120
	v_sub_f32_e32 v120, v179, v121
	v_exp_f32_e32 v120, v120
	v_sub_f32_e32 v171, v180, v121
	v_exp_f32_e32 v171, v171
	v_sub_f32_e32 v173, v181, v121
	v_exp_f32_e32 v173, v173
	v_add_f32_e32 v178, v170, v182
	v_add_f32_e32 v178, v120, v178
	v_add_f32_e32 v178, v171, v178
	v_add_f32_e32 v182, v173, v178
	v_sub_f32_e32 v178, v185, v121
	v_exp_f32_e32 v178, v178
	v_sub_f32_e32 v179, v187, v121
	v_exp_f32_e32 v179, v179
	v_sub_f32_e32 v180, v188, v121
	v_exp_f32_e32 v180, v180
	v_sub_f32_e32 v181, v205, v121
	v_exp_f32_e32 v181, v181
	v_add_f32_e32 v182, v178, v182
	v_add_f32_e32 v182, v179, v182
	v_add_f32_e32 v182, v180, v182
	v_add_f32_e32 v187, v181, v182
	v_sub_f32_e32 v182, v215, v121
	v_exp_f32_e32 v182, v182
	v_sub_f32_e32 v183, v216, v121
	v_exp_f32_e32 v183, v183
	v_sub_f32_e32 v184, v217, v121
	v_exp_f32_e32 v184, v184
	v_sub_f32_e32 v185, v218, v121
	v_exp_f32_e32 v185, v185
	v_add_f32_e32 v187, v182, v187
	v_add_f32_e32 v187, v183, v187
	v_add_f32_e32 v187, v184, v187
	v_add_f32_e32 v187, v185, v187
	ds_bpermute_b32 v188, v145, v187

; template <bool MASKED>
; DI bool attnA_tile_math(const f32x16& Su, const LAS float* bt, int qpos, int kpos0, int kvalid, bool meta_tile, int h, int lane, float& m, float& l, float& corr, bf16x8 (&bfrag)[2]) {
;     ...
;         const int row = (r & 3) + 8 * (r >> 2) + 4 * h;
;         const int dist = qpos - (kpos0 + row);
;         if (MASKED) {
;             const bool vis = (row < kvalid) && (dist >= 0) && (meta_tile || dist < 128);
;             const int di = dist < 0 ? 0 : (dist > 128 ? 128 : dist);
;             const float v = Su[r] * (0.125f * 1.4426950408889634f) + bt[di];
;             sc[r] = vis ? v : -1e30f;
;         } else sc[r] = Su[r] * (0.125f * 1.4426950408889634f) + bt[dist];
; DI void attnA_item(bf16_t* z, const float* sinks, int hp, int qs, LAS bf16_t* vs, const LAS float* btab, int lane) {
;     ...
;             for (int s = 0; s < 4; ++s) qf[s] = qs_lds[64 * (4 * u + s)];
.LfastA:
	v_sub_u32_e32 v212, v148, v211
	v_sub_u32_e32 v213, v150, v211
	v_sub_u32_e32 v214, v152, v211
	v_sub_u32_e32 v210, v158, v211
	v_sub_u32_e32 v209, v160, v211
	v_sub_u32_e32 v208, v162, v211
	ds_read_b128 v[66:69], v129 offset:6144
	ds_read_b128 v[120:123], v129 offset:7168
	ds_read_b128 v[168:171], v129 offset:8192
	ds_read_b128 v[178:181], v129 offset:9216
	s_waitcnt lgkmcnt(0)
	s_branch .LqkA
